# attention: context K/V LDS images filled by 16 concurrent LDS-DMA pieces per wave instead of 16 serialized load-wait-ds_write round trips
# speedup vs baseline: 1.0159x; 1.0012x over previous
; #define LAS __attribute__((address_space(3)))
; __global__ void __launch_bounds__(NTHREADS, 2) mega(Args args) {
;     ...
;                     { const int oc0 = (ML + b * CTX) >> 3;
;                       for (int ci = tid; ci < 4096; ci += NTHREADS) { const int o = ci >> 7, wq = ci & 127;
;                           const u32x4 kv = *(const u32x4*)(KTp + ((size_t)((oc0 + o) * NH + h)) * 1024 + wq * 8);
;                           *(LAS u32x4*)(lds + o * 2048 + (wq & ~15) * 16 + ((wq & 15) ^ (o & 2)) * 16) = kv;
;                           const u32x4 vv = *(const u32x4*)(VTp + ((size_t)((oc0 + o) * NH + h)) * 1024 + wq * 8);
;                           *(LAS u32x4*)(lds + 65536 + o * 2048 + wq * 16) = vv; }
.LBB9_659:
	s_ashr_i32 s4, s70, 6
	s_lshl_b32 s71, s4, 8
	s_bfe_u32 s72, s70, 0x40002
	s_addk_i32 s71, 0x2000
	s_barrier
	s_ashr_i32 s54, s71, 3
	s_lshl_b32 s54, s54, 4
	s_add_i32 s54, s54, s72
	s_lshl_b32 s54, s54, 11
	s_lshr_b32 s55, s57, 1
	s_lshl_b32 s55, s55, 15
	s_add_i32 s54, s54, s55
	s_and_b32 s55, s57, 1
	s_lshl_b32 s55, s55, 10
	s_add_i32 s54, s54, s55
	s_lshr_b32 s55, s57, 2
	s_lshl_b32 s55, s55, 1
	v_xor_b32_e32 v218, s55, v164
	v_lshlrev_b32_e32 v218, 4, v218
	v_lshlrev_b32_e32 v219, 4, v164
	v_add_u32_e32 v218, s54, v218
	v_add_u32_e32 v219, s54, v219
	ds_read_b64 v[220:221], v241 offset:192
	s_waitcnt lgkmcnt(0)
	v_add_co_u32_e32 v222, vcc, 0x21f00000, v220
	s_nop 1
	v_addc_co_u32_e32 v223, vcc, 0, v221, vcc
	v_add_co_u32_e32 v224, vcc, 0x24300000, v220
	s_nop 1
	v_addc_co_u32_e32 v225, vcc, 0, v221, vcc
	v_add_co_u32_e32 v222, vcc, v222, v218
	s_nop 1
	v_addc_co_u32_e32 v223, vcc, 0, v223, vcc
	v_add_co_u32_e32 v224, vcc, v224, v219
	s_nop 1
	v_addc_co_u32_e32 v225, vcc, 0, v225, vcc
	s_lshl_b32 s55, s57, 10
	s_add_i32 m0, s55, 0
	s_nop 0
	global_load_lds_dwordx4 v[222:223], off
	s_add_i32 m0, s55, 65536
	s_nop 0
	global_load_lds_dwordx4 v[224:225], off
	v_add_co_u32_e32 v222, vcc, 0x20000, v222
	s_nop 1
	v_addc_co_u32_e32 v223, vcc, 0, v223, vcc
	v_add_co_u32_e32 v224, vcc, 0x20000, v224
	s_nop 1
	v_addc_co_u32_e32 v225, vcc, 0, v225, vcc
	s_add_i32 m0, s55, 8192
	s_nop 0
	global_load_lds_dwordx4 v[222:223], off
	s_add_i32 m0, s55, 73728
	s_nop 0
	global_load_lds_dwordx4 v[224:225], off
	v_add_co_u32_e32 v222, vcc, 0x20000, v222
	s_nop 1
	v_addc_co_u32_e32 v223, vcc, 0, v223, vcc
	v_add_co_u32_e32 v224, vcc, 0x20000, v224
	s_nop 1
	v_addc_co_u32_e32 v225, vcc, 0, v225, vcc
	s_add_i32 m0, s55, 16384
	s_nop 0
	global_load_lds_dwordx4 v[222:223], off
	s_add_i32 m0, s55, 81920
	s_nop 0
	global_load_lds_dwordx4 v[224:225], off
	v_add_co_u32_e32 v222, vcc, 0x20000, v222
	s_nop 1
	v_addc_co_u32_e32 v223, vcc, 0, v223, vcc
	v_add_co_u32_e32 v224, vcc, 0x20000, v224
	s_nop 1
	v_addc_co_u32_e32 v225, vcc, 0, v225, vcc
	s_add_i32 m0, s55, 24576
	s_nop 0
	global_load_lds_dwordx4 v[222:223], off
	s_add_i32 m0, s55, 90112
	s_nop 0
	global_load_lds_dwordx4 v[224:225], off
	v_add_co_u32_e32 v222, vcc, 0x20000, v222
	s_nop 1
	v_addc_co_u32_e32 v223, vcc, 0, v223, vcc
	v_add_co_u32_e32 v224, vcc, 0x20000, v224
	s_nop 1
	v_addc_co_u32_e32 v225, vcc, 0, v225, vcc
	s_add_i32 m0, s55, 32768
	s_nop 0
	global_load_lds_dwordx4 v[222:223], off
	s_add_i32 m0, s55, 98304
	s_nop 0
	global_load_lds_dwordx4 v[224:225], off
	v_add_co_u32_e32 v222, vcc, 0x20000, v222
	s_nop 1
	v_addc_co_u32_e32 v223, vcc, 0, v223, vcc
	v_add_co_u32_e32 v224, vcc, 0x20000, v224
	s_nop 1
	v_addc_co_u32_e32 v225, vcc, 0, v225, vcc
	s_add_i32 m0, s55, 40960
	s_nop 0
	global_load_lds_dwordx4 v[222:223], off
	s_add_i32 m0, s55, 106496
	s_nop 0
	global_load_lds_dwordx4 v[224:225], off
	v_add_co_u32_e32 v222, vcc, 0x20000, v222
	s_nop 1
	v_addc_co_u32_e32 v223, vcc, 0, v223, vcc
	v_add_co_u32_e32 v224, vcc, 0x20000, v224
	s_nop 1
	v_addc_co_u32_e32 v225, vcc, 0, v225, vcc
	s_add_i32 m0, s55, 49152
	s_nop 0
	global_load_lds_dwordx4 v[222:223], off
	s_add_i32 m0, s55, 114688
	s_nop 0
	global_load_lds_dwordx4 v[224:225], off
	v_add_co_u32_e32 v222, vcc, 0x20000, v222
	s_nop 1
	v_addc_co_u32_e32 v223, vcc, 0, v223, vcc
	v_add_co_u32_e32 v224, vcc, 0x20000, v224
	s_nop 1
	v_addc_co_u32_e32 v225, vcc, 0, v225, vcc
	s_add_i32 m0, s55, 57344
	s_nop 0
	global_load_lds_dwordx4 v[222:223], off
	s_add_i32 m0, s55, 122880
	s_nop 0
	global_load_lds_dwordx4 v[224:225], off
	s_waitcnt vmcnt(0)
.LBB9_662:
	s_lshr_b32 s5, s70, 2
	s_and_saveexec_b64 s[50:51], s[40:41]
	s_cbranch_execz .LBB9_672
	s_mov_b64 s[34:35], -1
	v_mov_b32_e32 v2, v142
	v_mov_b32_e32 v4, v191
	s_and_saveexec_b64 s[52:53], s[42:43]
	s_cbranch_execz .LBB9_669
	s_mul_i32 s33, s72, 0x1d1
	s_mov_b32 s48, s33
	s_mov_b64 s[34:35], 0
	v_mov_b32_e32 v4, v185
	v_mov_b32_e32 v5, v192
	v_mov_b64_e32 v[2:3], v[142:143]
